# EpiIn epilogue: each lane computes the row norm for 2 rows only and gathers the 8 it needs with ds_bpermute (was 8 rows x 4 loads per lane, 4x redundant within the wave)
# speedup vs baseline: 1.0095x; 1.0041x over previous
.LBB0_219:
	v_lshl_add_u32 v142, s8, 8, v144
	s_and_b32 s9, s7, -4
	s_cmp_eq_u32 s9, 4
	s_cselect_b64 vcc, -1, 0
	s_lshl_b32 s46, s7, 8
	s_ashr_i32 s47, s46, 31
	s_lshl_b64 s[90:91], s[46:47], 1
	v_and_b32_e32 v141, 0x30, v217
	v_add_u32_e32 v141, v142, v141
	v_lshlrev_b32_e32 v140, 6, v141
	global_load_dwordx4 v[148:151], v140, s[54:55] offset:48
	global_load_dwordx4 v[152:155], v140, s[54:55] offset:32
	global_load_dwordx4 v[156:159], v140, s[54:55] offset:16
	global_load_dwordx4 v[160:163], v140, s[54:55]
	v_add_u32_e32 v141, 0x2000, v140
	global_load_dwordx4 v[164:167], v141, s[54:55] offset:48
	global_load_dwordx4 v[168:171], v141, s[54:55] offset:32
	global_load_dwordx4 v[172:175], v141, s[54:55] offset:16
	global_load_dwordx4 v[176:179], v141, s[54:55]
	v_cndmask_b32_e32 v147, 1.0, v221, vcc
	v_mov_b64_e32 v[246:247], s[82:83]
	v_lshl_add_u64 v[246:247], v[246:247], 0, s[90:91]
	v_lshl_add_u64 v[246:247], v[246:247], 0, s[92:93]
	v_lshl_add_u64 v[246:247], v[246:247], 0, v[194:195]
	v_and_b32_e32 v180, 15, v217
	v_lshlrev_b32_e32 v180, 2, v180
	s_waitcnt vmcnt(4)
	v_add_f32_e32 v160, v160, v161
	v_add_f32_e32 v162, v162, v163
	v_add_f32_e32 v156, v156, v157
	v_add_f32_e32 v158, v158, v159
	v_add_f32_e32 v152, v152, v153
	v_add_f32_e32 v154, v154, v155
	v_add_f32_e32 v148, v148, v149
	v_add_f32_e32 v150, v150, v151
	v_add_f32_e32 v160, v160, v162
	v_add_f32_e32 v156, v156, v158
	v_add_f32_e32 v152, v152, v154
	v_add_f32_e32 v148, v148, v150
	v_add_f32_e32 v160, v160, v156
	v_add_f32_e32 v160, v160, v152
	v_add_f32_e32 v160, v160, v148
	v_fmamk_f32 v160, v160, 0x3a800000, v189
	v_cmp_gt_f32_e32 vcc, s13, v160
	v_mul_f32_e32 v161, 0x4b800000, v160
	s_nop 0
	v_cndmask_b32_e32 v160, v160, v161, vcc
	v_rsq_f32_e32 v160, v160
	s_nop 0
	v_mul_f32_e32 v161, 0x45800000, v160
	v_cndmask_b32_e32 v160, v160, v161, vcc
	ds_bpermute_b32 v208, v180, v160
	ds_bpermute_b32 v209, v180, v160 offset:64
	ds_bpermute_b32 v210, v180, v160 offset:128
	ds_bpermute_b32 v211, v180, v160 offset:192
	s_waitcnt vmcnt(0)
	v_add_f32_e32 v176, v176, v177
	v_add_f32_e32 v178, v178, v179
	v_add_f32_e32 v172, v172, v173
	v_add_f32_e32 v174, v174, v175
	v_add_f32_e32 v168, v168, v169
	v_add_f32_e32 v170, v170, v171
	v_add_f32_e32 v164, v164, v165
	v_add_f32_e32 v166, v166, v167
	v_add_f32_e32 v176, v176, v178
	v_add_f32_e32 v172, v172, v174
	v_add_f32_e32 v168, v168, v170
	v_add_f32_e32 v164, v164, v166
	v_add_f32_e32 v176, v176, v172
	v_add_f32_e32 v176, v176, v168
	v_add_f32_e32 v176, v176, v164
	v_fmamk_f32 v176, v176, 0x3a800000, v189
	v_cmp_gt_f32_e32 vcc, s13, v176
	v_mul_f32_e32 v177, 0x4b800000, v176
	s_nop 0
	v_cndmask_b32_e32 v176, v176, v177, vcc
	v_rsq_f32_e32 v176, v176
	s_nop 0
	v_mul_f32_e32 v177, 0x45800000, v176
	v_cndmask_b32_e32 v176, v176, v177, vcc
	ds_bpermute_b32 v212, v180, v176
	ds_bpermute_b32 v213, v180, v176 offset:64
	ds_bpermute_b32 v214, v180, v176 offset:128
	ds_bpermute_b32 v215, v180, v176 offset:192
	s_waitcnt lgkmcnt(7)
	v_mul_f32_e32 v248, v147, v208
	v_mad_i64_i32 v[244:245], s[8:9], v142, s14, v[246:247]
	v_pk_mul_f32 v[124:125], v[124:125], v[248:249] op_sel_hi:[1,0]
	v_pk_mul_f32 v[126:127], v[126:127], v[248:249] op_sel_hi:[1,0]
	v_pk_mul_f32 v[120:121], v[120:121], v[248:249] op_sel_hi:[1,0]
	v_pk_mul_f32 v[122:123], v[122:123], v[248:249] op_sel_hi:[1,0]
	v_cvt_pk_bf16_f32 v124, v124, v125
	v_cvt_pk_bf16_f32 v125, v126, v127
	v_cvt_pk_bf16_f32 v126, v120, v121
	v_cvt_pk_bf16_f32 v127, v122, v123
	global_store_dwordx4 v[244:245], v[124:127], off nt
	v_pk_mul_f32 v[116:117], v[116:117], v[248:249] op_sel_hi:[1,0]
	v_pk_mul_f32 v[118:119], v[118:119], v[248:249] op_sel_hi:[1,0]
	v_pk_mul_f32 v[112:113], v[112:113], v[248:249] op_sel_hi:[1,0]
	v_pk_mul_f32 v[114:115], v[114:115], v[248:249] op_sel_hi:[1,0]
	v_cvt_pk_bf16_f32 v116, v116, v117
	v_cvt_pk_bf16_f32 v117, v118, v119
	v_cvt_pk_bf16_f32 v118, v112, v113
	v_cvt_pk_bf16_f32 v119, v114, v115
	global_store_dwordx4 v[244:245], v[116:119], off offset:256 nt
	s_waitcnt lgkmcnt(6)
	v_mul_f32_e32 v248, v147, v209
	v_add_u32_e32 v141, 0x10, v142
	v_mad_i64_i32 v[244:245], s[8:9], v141, s14, v[246:247]
	v_pk_mul_f32 v[108:109], v[108:109], v[248:249] op_sel_hi:[1,0]
	v_pk_mul_f32 v[110:111], v[110:111], v[248:249] op_sel_hi:[1,0]
	v_pk_mul_f32 v[104:105], v[104:105], v[248:249] op_sel_hi:[1,0]
	v_pk_mul_f32 v[106:107], v[106:107], v[248:249] op_sel_hi:[1,0]
	v_cvt_pk_bf16_f32 v108, v108, v109
	v_cvt_pk_bf16_f32 v109, v110, v111
	v_cvt_pk_bf16_f32 v110, v104, v105
	v_cvt_pk_bf16_f32 v111, v106, v107
	global_store_dwordx4 v[244:245], v[108:111], off nt
	v_pk_mul_f32 v[100:101], v[100:101], v[248:249] op_sel_hi:[1,0]
	v_pk_mul_f32 v[102:103], v[102:103], v[248:249] op_sel_hi:[1,0]
	v_pk_mul_f32 v[96:97], v[96:97], v[248:249] op_sel_hi:[1,0]
	v_pk_mul_f32 v[98:99], v[98:99], v[248:249] op_sel_hi:[1,0]
	v_cvt_pk_bf16_f32 v100, v100, v101
	v_cvt_pk_bf16_f32 v101, v102, v103
	v_cvt_pk_bf16_f32 v102, v96, v97
	v_cvt_pk_bf16_f32 v103, v98, v99
	global_store_dwordx4 v[244:245], v[100:103], off offset:256 nt
	s_waitcnt lgkmcnt(5)
	v_mul_f32_e32 v248, v147, v210
	v_add_u32_e32 v141, 0x20, v142
	v_mad_i64_i32 v[244:245], s[8:9], v141, s14, v[246:247]
	v_pk_mul_f32 v[92:93], v[92:93], v[248:249] op_sel_hi:[1,0]
	v_pk_mul_f32 v[94:95], v[94:95], v[248:249] op_sel_hi:[1,0]
	v_pk_mul_f32 v[88:89], v[88:89], v[248:249] op_sel_hi:[1,0]
	v_pk_mul_f32 v[90:91], v[90:91], v[248:249] op_sel_hi:[1,0]
	v_cvt_pk_bf16_f32 v92, v92, v93
	v_cvt_pk_bf16_f32 v93, v94, v95
	v_cvt_pk_bf16_f32 v94, v88, v89
	v_cvt_pk_bf16_f32 v95, v90, v91
	global_store_dwordx4 v[244:245], v[92:95], off nt
	v_pk_mul_f32 v[84:85], v[84:85], v[248:249] op_sel_hi:[1,0]
	v_pk_mul_f32 v[86:87], v[86:87], v[248:249] op_sel_hi:[1,0]
	v_pk_mul_f32 v[80:81], v[80:81], v[248:249] op_sel_hi:[1,0]
	v_pk_mul_f32 v[82:83], v[82:83], v[248:249] op_sel_hi:[1,0]
	v_cvt_pk_bf16_f32 v84, v84, v85
	v_cvt_pk_bf16_f32 v85, v86, v87
	v_cvt_pk_bf16_f32 v86, v80, v81
	v_cvt_pk_bf16_f32 v87, v82, v83
	global_store_dwordx4 v[244:245], v[84:87], off offset:256 nt
	s_waitcnt lgkmcnt(4)
	v_mul_f32_e32 v248, v147, v211
	v_add_u32_e32 v141, 0x30, v142
	v_mad_i64_i32 v[244:245], s[8:9], v141, s14, v[246:247]
	v_pk_mul_f32 v[76:77], v[76:77], v[248:249] op_sel_hi:[1,0]
	v_pk_mul_f32 v[78:79], v[78:79], v[248:249] op_sel_hi:[1,0]
	v_pk_mul_f32 v[72:73], v[72:73], v[248:249] op_sel_hi:[1,0]
	v_pk_mul_f32 v[74:75], v[74:75], v[248:249] op_sel_hi:[1,0]
	v_cvt_pk_bf16_f32 v76, v76, v77
	v_cvt_pk_bf16_f32 v77, v78, v79
	v_cvt_pk_bf16_f32 v78, v72, v73
	v_cvt_pk_bf16_f32 v79, v74, v75
	global_store_dwordx4 v[244:245], v[76:79], off nt
	v_pk_mul_f32 v[68:69], v[68:69], v[248:249] op_sel_hi:[1,0]
	v_pk_mul_f32 v[70:71], v[70:71], v[248:249] op_sel_hi:[1,0]
	v_pk_mul_f32 v[64:65], v[64:65], v[248:249] op_sel_hi:[1,0]
	v_pk_mul_f32 v[66:67], v[66:67], v[248:249] op_sel_hi:[1,0]
	v_cvt_pk_bf16_f32 v68, v68, v69
	v_cvt_pk_bf16_f32 v69, v70, v71
	v_cvt_pk_bf16_f32 v70, v64, v65
	v_cvt_pk_bf16_f32 v71, v66, v67
	global_store_dwordx4 v[244:245], v[68:71], off offset:256 nt
	s_waitcnt lgkmcnt(3)
	v_mul_f32_e32 v248, v147, v212
	v_add_u32_e32 v141, 0x80, v142
	v_mad_i64_i32 v[244:245], s[8:9], v141, s14, v[246:247]
	v_pk_mul_f32 v[60:61], v[60:61], v[248:249] op_sel_hi:[1,0]
	v_pk_mul_f32 v[62:63], v[62:63], v[248:249] op_sel_hi:[1,0]
	v_pk_mul_f32 v[56:57], v[56:57], v[248:249] op_sel_hi:[1,0]
	v_pk_mul_f32 v[58:59], v[58:59], v[248:249] op_sel_hi:[1,0]
	v_cvt_pk_bf16_f32 v60, v60, v61
	v_cvt_pk_bf16_f32 v61, v62, v63
	v_cvt_pk_bf16_f32 v62, v56, v57
	v_cvt_pk_bf16_f32 v63, v58, v59
	global_store_dwordx4 v[244:245], v[60:63], off nt
	v_pk_mul_f32 v[52:53], v[52:53], v[248:249] op_sel_hi:[1,0]
	v_pk_mul_f32 v[54:55], v[54:55], v[248:249] op_sel_hi:[1,0]
	v_pk_mul_f32 v[48:49], v[48:49], v[248:249] op_sel_hi:[1,0]
	v_pk_mul_f32 v[50:51], v[50:51], v[248:249] op_sel_hi:[1,0]
	v_cvt_pk_bf16_f32 v52, v52, v53
	v_cvt_pk_bf16_f32 v53, v54, v55
	v_cvt_pk_bf16_f32 v54, v48, v49
	v_cvt_pk_bf16_f32 v55, v50, v51
	global_store_dwordx4 v[244:245], v[52:55], off offset:256 nt
	s_waitcnt lgkmcnt(2)
	v_mul_f32_e32 v248, v147, v213
	v_add_u32_e32 v141, 0x90, v142
	v_mad_i64_i32 v[244:245], s[8:9], v141, s14, v[246:247]
	v_pk_mul_f32 v[44:45], v[44:45], v[248:249] op_sel_hi:[1,0]
	v_pk_mul_f32 v[46:47], v[46:47], v[248:249] op_sel_hi:[1,0]
	v_pk_mul_f32 v[40:41], v[40:41], v[248:249] op_sel_hi:[1,0]
	v_pk_mul_f32 v[42:43], v[42:43], v[248:249] op_sel_hi:[1,0]
	v_cvt_pk_bf16_f32 v44, v44, v45
	v_cvt_pk_bf16_f32 v45, v46, v47
	v_cvt_pk_bf16_f32 v46, v40, v41
	v_cvt_pk_bf16_f32 v47, v42, v43
	global_store_dwordx4 v[244:245], v[44:47], off nt
	v_pk_mul_f32 v[36:37], v[36:37], v[248:249] op_sel_hi:[1,0]
	v_pk_mul_f32 v[38:39], v[38:39], v[248:249] op_sel_hi:[1,0]
	v_pk_mul_f32 v[32:33], v[32:33], v[248:249] op_sel_hi:[1,0]
	v_pk_mul_f32 v[34:35], v[34:35], v[248:249] op_sel_hi:[1,0]
	v_cvt_pk_bf16_f32 v36, v36, v37
	v_cvt_pk_bf16_f32 v37, v38, v39
	v_cvt_pk_bf16_f32 v38, v32, v33
	v_cvt_pk_bf16_f32 v39, v34, v35
	global_store_dwordx4 v[244:245], v[36:39], off offset:256 nt
	s_waitcnt lgkmcnt(1)
	v_mul_f32_e32 v248, v147, v214
	v_add_u32_e32 v141, 0xa0, v142
	v_mad_i64_i32 v[244:245], s[8:9], v141, s14, v[246:247]
	v_pk_mul_f32 v[28:29], v[28:29], v[248:249] op_sel_hi:[1,0]
	v_pk_mul_f32 v[30:31], v[30:31], v[248:249] op_sel_hi:[1,0]
	v_pk_mul_f32 v[24:25], v[24:25], v[248:249] op_sel_hi:[1,0]
	v_pk_mul_f32 v[26:27], v[26:27], v[248:249] op_sel_hi:[1,0]
	v_cvt_pk_bf16_f32 v28, v28, v29
	v_cvt_pk_bf16_f32 v29, v30, v31
	v_cvt_pk_bf16_f32 v30, v24, v25
	v_cvt_pk_bf16_f32 v31, v26, v27
	global_store_dwordx4 v[244:245], v[28:31], off nt
	v_pk_mul_f32 v[20:21], v[20:21], v[248:249] op_sel_hi:[1,0]
	v_pk_mul_f32 v[22:23], v[22:23], v[248:249] op_sel_hi:[1,0]
	v_pk_mul_f32 v[16:17], v[16:17], v[248:249] op_sel_hi:[1,0]
	v_pk_mul_f32 v[18:19], v[18:19], v[248:249] op_sel_hi:[1,0]
	v_cvt_pk_bf16_f32 v20, v20, v21
	v_cvt_pk_bf16_f32 v21, v22, v23
	v_cvt_pk_bf16_f32 v22, v16, v17
	v_cvt_pk_bf16_f32 v23, v18, v19
	global_store_dwordx4 v[244:245], v[20:23], off offset:256 nt
	s_waitcnt lgkmcnt(0)
	v_mul_f32_e32 v248, v147, v215
	v_add_u32_e32 v141, 0xb0, v142
	v_mad_i64_i32 v[244:245], s[8:9], v141, s14, v[246:247]
	v_pk_mul_f32 v[12:13], v[12:13], v[248:249] op_sel_hi:[1,0]
	v_pk_mul_f32 v[14:15], v[14:15], v[248:249] op_sel_hi:[1,0]
	v_pk_mul_f32 v[8:9], v[8:9], v[248:249] op_sel_hi:[1,0]
	v_pk_mul_f32 v[10:11], v[10:11], v[248:249] op_sel_hi:[1,0]
	v_cvt_pk_bf16_f32 v12, v12, v13
	v_cvt_pk_bf16_f32 v13, v14, v15
	v_cvt_pk_bf16_f32 v14, v8, v9
	v_cvt_pk_bf16_f32 v15, v10, v11
	global_store_dwordx4 v[244:245], v[12:15], off nt
	v_pk_mul_f32 v[4:5], v[4:5], v[248:249] op_sel_hi:[1,0]
	v_pk_mul_f32 v[6:7], v[6:7], v[248:249] op_sel_hi:[1,0]
	v_pk_mul_f32 v[0:1], v[0:1], v[248:249] op_sel_hi:[1,0]
	v_pk_mul_f32 v[2:3], v[2:3], v[248:249] op_sel_hi:[1,0]
	v_cvt_pk_bf16_f32 v4, v4, v5
	v_cvt_pk_bf16_f32 v5, v6, v7
	v_cvt_pk_bf16_f32 v6, v0, v1
	v_cvt_pk_bf16_f32 v7, v2, v3
	s_mov_b64 s[90:91], -1
	s_andn2_b64 vcc, exec, s[36:37]
	global_store_dwordx4 v[244:245], v[4:7], off offset:256 nt
	s_cbranch_vccnz .LBB0_212
	s_andn2_b64 vcc, exec, s[0:1]
	s_cbranch_vccnz .LBB0_211
	s_barrier
	s_branch .LBB0_211
